# g3early: S3 global counter arrival moved to the end of each P3 K-loop (ACT reads done), S3 waits for 2x grid in wave 1 in parallel with wave 0's class slot barrier
# speedup vs baseline: 1.0042x; 1.0042x over previous
.LBB0_255:
	v_readfirstlane_b32 s32, v0
	s_nop 0
	s_lshr_b32 s32, s32, 6
	s_cmp_lt_i32 s30, 4
	s_cselect_b64 s[0:1], -1, 0
	s_add_u32 s8, s28, 0x500000
	s_addc_u32 s9, s29, 0
	s_add_u32 s38, s28, 0x7000000
	s_addc_u32 s39, s29, 0
	s_and_b64 s[4:5], s[0:1], s[2:3]
	s_andn2_b64 vcc, exec, s[4:5]
	s_cbranch_vccnz .LBB0_298
	s_cmpk_lt_i32 s24, 0x200
	s_cselect_b64 s[0:1], -1, 0
	s_cmpk_gt_i32 s24, 0x1ff
	v_readfirstlane_b32 s2, v0
	s_cbranch_scc1 .LBB0_258
	s_ashr_i32 s3, s24, 31
	s_lshr_b32 s3, s3, 29
	s_add_i32 s3, s24, s3
	s_and_b32 s10, s3, -8
	s_sub_i32 s10, s24, s10
	s_lshl_b32 s12, s10, 6
	s_ashr_i32 s3, s3, 3
	s_mul_i32 s11, s10, 0x41
	s_cmp_lt_i32 s10, 0
	s_cselect_b32 s10, s11, s12
	s_add_i32 s3, s10, s3
	s_ashr_i32 s10, s3, 31
	s_lshr_b32 s10, s10, 27
	s_add_i32 s10, s3, s10
	s_ashr_i32 s11, s10, 5
	s_andn2_b32 s10, s10, 31
	s_sub_i32 s3, s3, s10
	s_bfe_i32 s10, s3, 0x80000
	s_bfe_u32 s10, s10, 0x3000c
	s_add_i32 s10, s3, s10
	s_bfe_i32 s12, s10, 0x80000
	s_and_b32 s10, s10, 0xf8
	s_sub_i32 s3, s3, s10
	s_lshl_b32 s11, s11, 3
	s_sext_i32_i16 s12, s12
	s_sext_i32_i8 s3, s3
	s_add_i32 s35, s11, s3
	s_ashr_i32 s34, s12, 3

.Lpeel_exit_275:
	s_cmp_lg_u32 s32, 0
	s_cbranch_scc1 .Lg3e_skip
	s_mov_b64 s[98:99], exec
	s_mov_b64 exec, 1
	v_mov_b32_e32 v206, 0x640c
	v_mov_b32_e32 v207, 1
	global_atomic_add v206, v207, s[28:29]
	s_mov_b64 exec, s[98:99]

.Llb_loc_s3:
	v_cmp_gt_u32_e32 vcc, 32, v0
	s_and_saveexec_b64 s[2:3], vcc
	s_cbranch_execz .Lg3w_s3
	v_readlane_b32 s4, v254, 14
	v_readlane_b32 s10, v254, 12
	v_readlane_b32 s11, v254, 13
	s_lshl_b32 s4, s4, 7
	s_add_u32 s4, s10, s4
	s_addc_u32 s5, s11, 0
	s_lshr_b32 s98, s24, 3
	s_lshl_b32 s98, s98, 2
	s_add_i32 s98, s98, 0x4000
	v_mov_b32_e32 v3, s98
	v_mov_b32_e32 v4, 3
	global_store_dword v3, v4, s[4:5]
	v_lshlrev_b32_e32 v3, 2, v0
	v_add_u32_e32 v3, 0x4000, v3
	s_mov_b32 s99, 0
.Llb_spin_s3:
	global_load_dword v2, v3, s[4:5] sc1
	s_waitcnt vmcnt(0)
	v_cmp_gt_u32_e32 vcc, 3, v2
	s_cbranch_vccz .Llb_acq_s3
	s_sleep 1
	s_add_i32 s99, s99, 1
	s_cmp_lt_u32 s99, 0x40000
	s_cbranch_scc1 .Llb_spin_s3
.Llb_acq_s3:
	s_waitcnt vmcnt(0)
	s_branch .Llb_done_s3
.Lg3w_s3:
	v_readfirstlane_b32 s98, v0
	s_nop 0
	s_cmp_lg_u32 s98, 64
	s_cbranch_scc1 .Llb_done_s3
	s_mov_b64 exec, 1
	v_mov_b32_e32 v5, 0x640c
	s_lshl_b32 s98, s25, 1
	s_mov_b32 s99, 0
.Llb_g3_s3:
	global_load_dword v4, v5, s[28:29] sc1
	s_waitcnt vmcnt(0)
	v_cmp_le_u32_e32 vcc, s98, v4
	s_cbranch_vccnz .Llb_g3d_s3
	s_sleep 1
	s_add_i32 s99, s99, 1
	s_cmp_lt_u32 s99, 0x40000
	s_cbranch_scc1 .Llb_g3_s3
.Llb_g3d_s3:
	s_mov_b64 exec, 0
